# EpiRes epilogues (w_o, w_down): serial load/wait/store ladder replaced by 2-group software pipeline with counted vmcnt
# speedup vs baseline: 1.0061x; 1.0061x over previous
;     __device__ __forceinline__ void operator()(const f32x4 (&acc)[2][2][4][2], const Unit& u, int wr, int wc, int fr, int fq) const {
;         const int row0 = u.pm * BM + wr * 64 + fr, col0 = u.pn * BM + wc * 32 + 4 * fq;
;         f32x4 gv[2][2];
; #pragma unroll
;         for (int bj = 0; bj < 2; ++bj)
; #pragma unroll
;             for (int n = 0; n < 2; ++n) gv[bj][n] = *(const f32x4*)(gate + col0 + bj * HALF + n * 16) + 1.0f;
; #pragma unroll
;         for (int ai = 0; ai < 2; ++ai)
; #pragma unroll
;             for (int m = 0; m < 4; ++m) { const size_t off = (size_t)(row0 + ai * HALF + m * 16) * ldc + col0;
; #pragma unroll
;                 for (int bj = 0; bj < 2; ++bj)
; #pragma unroll
;                     for (int n = 0; n < 2; ++n) { const f32x4 xr = *(const f32x4*)(xres + off + bj * HALF + n * 16);
;                         *(f32x4*)(z + off + bj * HALF + n * 16) = xr * alpha + gv[bj][n] * acc[ai][bj][m][n]; }
;                 if (m == 3) asm volatile("" ::: "memory"); }
.LBB0_1017:
	v_lshl_or_b32 v158, s68, 8, v164
	v_ashrrev_i32_e32 v159, 31, v158
	v_lshl_add_u64 v[156:157], v[158:159], 2, s[18:19]
	global_load_dwordx4 v[140:143], v[156:157], off
	global_load_dwordx4 v[144:147], v[156:157], off offset:64
	global_load_dwordx4 v[148:151], v[156:157], off offset:512
	global_load_dwordx4 v[152:155], v[156:157], off offset:576
	v_lshl_add_u32 v160, s59, 8, v162
	v_ashrrev_i32_e32 v161, 31, v160
	s_mov_b32 s26, 0x3fb504f3
	s_and_b64 vcc, exec, s[4:5]
	v_lshlrev_b64 v[156:157], 11, v[160:161]
	v_lshl_add_u64 v[156:157], v[156:157], 0, v[158:159]
	v_lshlrev_b64 v[156:157], 2, v[156:157]
	v_lshl_add_u64 v[182:183], s[2:3], 0, v[156:157]
	v_lshl_add_u64 v[184:185], s[16:17], 0, v[156:157]
	s_mov_b64 s[28:29], 0x20000
	global_load_dwordx4 v[166:169], v[182:183], off
	global_load_dwordx4 v[170:173], v[182:183], off offset:64
	global_load_dwordx4 v[174:177], v[182:183], off offset:512
	global_load_dwordx4 v[178:181], v[182:183], off offset:576
	v_lshl_add_u64 v[182:183], v[182:183], 0, s[28:29]
	global_load_dwordx4 v[194:197], v[182:183], off
	global_load_dwordx4 v[198:201], v[182:183], off offset:64
	global_load_dwordx4 v[202:205], v[182:183], off offset:512
	global_load_dwordx4 v[206:209], v[182:183], off offset:576
	v_lshl_add_u64 v[182:183], v[182:183], 0, s[28:29]
	s_waitcnt vmcnt(8)
	v_pk_add_f32 v[140:141], v[140:141], 1.0 op_sel_hi:[1,0]
	v_pk_add_f32 v[142:143], v[142:143], 1.0 op_sel_hi:[1,0]
	v_pk_add_f32 v[144:145], v[144:145], 1.0 op_sel_hi:[1,0]
	v_pk_add_f32 v[146:147], v[146:147], 1.0 op_sel_hi:[1,0]
	v_pk_add_f32 v[148:149], v[148:149], 1.0 op_sel_hi:[1,0]
	v_pk_add_f32 v[150:151], v[150:151], 1.0 op_sel_hi:[1,0]
	v_pk_add_f32 v[152:153], v[152:153], 1.0 op_sel_hi:[1,0]
	v_pk_add_f32 v[154:155], v[154:155], 1.0 op_sel_hi:[1,0]
	s_waitcnt vmcnt(4)
	v_pk_mul_f32 v[168:169], v[168:169], s[26:27] op_sel_hi:[1,0]
	v_pk_mul_f32 v[166:167], v[166:167], s[26:27] op_sel_hi:[1,0]
	v_pk_fma_f32 v[128:129], v[128:129], v[142:143], v[168:169]
	v_pk_fma_f32 v[126:127], v[126:127], v[140:141], v[166:167]
	global_store_dwordx4 v[184:185], v[126:129], off
	v_pk_mul_f32 v[172:173], v[172:173], s[26:27] op_sel_hi:[1,0]
	v_pk_mul_f32 v[170:171], v[170:171], s[26:27] op_sel_hi:[1,0]
	v_pk_fma_f32 v[124:125], v[124:125], v[146:147], v[172:173]
	v_pk_fma_f32 v[122:123], v[122:123], v[144:145], v[170:171]
	global_store_dwordx4 v[184:185], v[122:125], off offset:64
	v_pk_mul_f32 v[176:177], v[176:177], s[26:27] op_sel_hi:[1,0]
	v_pk_mul_f32 v[174:175], v[174:175], s[26:27] op_sel_hi:[1,0]
	v_pk_fma_f32 v[120:121], v[120:121], v[150:151], v[176:177]
	v_pk_fma_f32 v[118:119], v[118:119], v[148:149], v[174:175]
	global_store_dwordx4 v[184:185], v[118:121], off offset:512
	v_pk_mul_f32 v[180:181], v[180:181], s[26:27] op_sel_hi:[1,0]
	v_pk_mul_f32 v[178:179], v[178:179], s[26:27] op_sel_hi:[1,0]
	v_pk_fma_f32 v[116:117], v[116:117], v[154:155], v[180:181]
	v_pk_fma_f32 v[114:115], v[114:115], v[152:153], v[178:179]
	global_store_dwordx4 v[184:185], v[114:117], off offset:576
	v_lshl_add_u64 v[184:185], v[184:185], 0, s[28:29]
	global_load_dwordx4 v[166:169], v[182:183], off
	global_load_dwordx4 v[170:173], v[182:183], off offset:64
	global_load_dwordx4 v[174:177], v[182:183], off offset:512
	global_load_dwordx4 v[178:181], v[182:183], off offset:576
	v_lshl_add_u64 v[182:183], v[182:183], 0, s[28:29]
	s_waitcnt vmcnt(8)
	v_pk_mul_f32 v[196:197], v[196:197], s[26:27] op_sel_hi:[1,0]
	v_pk_mul_f32 v[194:195], v[194:195], s[26:27] op_sel_hi:[1,0]
	v_pk_fma_f32 v[112:113], v[112:113], v[142:143], v[196:197]
	v_pk_fma_f32 v[110:111], v[110:111], v[140:141], v[194:195]
	global_store_dwordx4 v[184:185], v[110:113], off
	v_pk_mul_f32 v[200:201], v[200:201], s[26:27] op_sel_hi:[1,0]
	v_pk_mul_f32 v[198:199], v[198:199], s[26:27] op_sel_hi:[1,0]
	v_pk_fma_f32 v[108:109], v[108:109], v[146:147], v[200:201]
	v_pk_fma_f32 v[106:107], v[106:107], v[144:145], v[198:199]
	global_store_dwordx4 v[184:185], v[106:109], off offset:64
	v_pk_mul_f32 v[204:205], v[204:205], s[26:27] op_sel_hi:[1,0]
	v_pk_mul_f32 v[202:203], v[202:203], s[26:27] op_sel_hi:[1,0]
	v_pk_fma_f32 v[104:105], v[104:105], v[150:151], v[204:205]
	v_pk_fma_f32 v[102:103], v[102:103], v[148:149], v[202:203]
	global_store_dwordx4 v[184:185], v[102:105], off offset:512
	v_pk_mul_f32 v[208:209], v[208:209], s[26:27] op_sel_hi:[1,0]
	v_pk_mul_f32 v[206:207], v[206:207], s[26:27] op_sel_hi:[1,0]
	v_pk_fma_f32 v[100:101], v[100:101], v[154:155], v[208:209]
	v_pk_fma_f32 v[98:99], v[98:99], v[152:153], v[206:207]
	global_store_dwordx4 v[184:185], v[98:101], off offset:576
	v_lshl_add_u64 v[184:185], v[184:185], 0, s[28:29]
	global_load_dwordx4 v[194:197], v[182:183], off
	global_load_dwordx4 v[198:201], v[182:183], off offset:64
	global_load_dwordx4 v[202:205], v[182:183], off offset:512
	global_load_dwordx4 v[206:209], v[182:183], off offset:576
	s_mov_b64 s[28:29], 0xa0000
	v_lshl_add_u64 v[182:183], v[182:183], 0, s[28:29]
	s_mov_b64 s[28:29], 0x20000
	s_waitcnt vmcnt(8)
;     __device__ __forceinline__ void operator()(const f32x4 (&acc)[2][2][4][2], const Unit& u, int wr, int wc, int fr, int fq) const {
;     ...
;             for (int m = 0; m < 4; ++m) { const size_t off = (size_t)(row0 + ai * HALF + m * 16) * ldc + col0;
; #pragma unroll
;                 for (int bj = 0; bj < 2; ++bj)
; #pragma unroll
;                     for (int n = 0; n < 2; ++n) { const f32x4 xr = *(const f32x4*)(xres + off + bj * HALF + n * 16);
;                         *(f32x4*)(z + off + bj * HALF + n * 16) = xr * alpha + gv[bj][n] * acc[ai][bj][m][n]; }
	v_pk_mul_f32 v[168:169], v[168:169], s[26:27] op_sel_hi:[1,0]
	v_pk_mul_f32 v[166:167], v[166:167], s[26:27] op_sel_hi:[1,0]
	v_pk_fma_f32 v[96:97], v[96:97], v[142:143], v[168:169]
	v_pk_fma_f32 v[94:95], v[94:95], v[140:141], v[166:167]
	global_store_dwordx4 v[184:185], v[94:97], off
	v_pk_mul_f32 v[172:173], v[172:173], s[26:27] op_sel_hi:[1,0]
	v_pk_mul_f32 v[170:171], v[170:171], s[26:27] op_sel_hi:[1,0]
	v_pk_fma_f32 v[92:93], v[92:93], v[146:147], v[172:173]
	v_pk_fma_f32 v[90:91], v[90:91], v[144:145], v[170:171]
	global_store_dwordx4 v[184:185], v[90:93], off offset:64
	v_pk_mul_f32 v[176:177], v[176:177], s[26:27] op_sel_hi:[1,0]
	v_pk_mul_f32 v[174:175], v[174:175], s[26:27] op_sel_hi:[1,0]
	v_pk_fma_f32 v[88:89], v[88:89], v[150:151], v[176:177]
	v_pk_fma_f32 v[86:87], v[86:87], v[148:149], v[174:175]
	global_store_dwordx4 v[184:185], v[86:89], off offset:512
	v_pk_mul_f32 v[180:181], v[180:181], s[26:27] op_sel_hi:[1,0]
	v_pk_mul_f32 v[178:179], v[178:179], s[26:27] op_sel_hi:[1,0]
	v_pk_fma_f32 v[84:85], v[84:85], v[154:155], v[180:181]
	v_pk_fma_f32 v[82:83], v[82:83], v[152:153], v[178:179]
	global_store_dwordx4 v[184:185], v[82:85], off offset:576
	v_lshl_add_u64 v[184:185], v[184:185], 0, s[28:29]
	global_load_dwordx4 v[166:169], v[182:183], off
	global_load_dwordx4 v[170:173], v[182:183], off offset:64
	global_load_dwordx4 v[174:177], v[182:183], off offset:512
	global_load_dwordx4 v[178:181], v[182:183], off offset:576
	v_lshl_add_u64 v[182:183], v[182:183], 0, s[28:29]
	s_waitcnt vmcnt(8)
	v_pk_mul_f32 v[196:197], v[196:197], s[26:27] op_sel_hi:[1,0]
	v_pk_mul_f32 v[194:195], v[194:195], s[26:27] op_sel_hi:[1,0]
	v_pk_fma_f32 v[80:81], v[80:81], v[142:143], v[196:197]
	v_pk_fma_f32 v[78:79], v[78:79], v[140:141], v[194:195]
	global_store_dwordx4 v[184:185], v[78:81], off
	v_pk_mul_f32 v[200:201], v[200:201], s[26:27] op_sel_hi:[1,0]
	v_pk_mul_f32 v[198:199], v[198:199], s[26:27] op_sel_hi:[1,0]
	v_pk_fma_f32 v[76:77], v[76:77], v[146:147], v[200:201]
	v_pk_fma_f32 v[74:75], v[74:75], v[144:145], v[198:199]
	global_store_dwordx4 v[184:185], v[74:77], off offset:64
	v_pk_mul_f32 v[204:205], v[204:205], s[26:27] op_sel_hi:[1,0]
	v_pk_mul_f32 v[202:203], v[202:203], s[26:27] op_sel_hi:[1,0]
	v_pk_fma_f32 v[72:73], v[72:73], v[150:151], v[204:205]
	v_pk_fma_f32 v[70:71], v[70:71], v[148:149], v[202:203]
	global_store_dwordx4 v[184:185], v[70:73], off offset:512
	v_pk_mul_f32 v[208:209], v[208:209], s[26:27] op_sel_hi:[1,0]
	v_pk_mul_f32 v[206:207], v[206:207], s[26:27] op_sel_hi:[1,0]
	v_pk_fma_f32 v[68:69], v[68:69], v[154:155], v[208:209]
	v_pk_fma_f32 v[66:67], v[66:67], v[152:153], v[206:207]
	global_store_dwordx4 v[184:185], v[66:69], off offset:576
	s_mov_b64 s[28:29], 0xa0000
	v_lshl_add_u64 v[184:185], v[184:185], 0, s[28:29]
	s_mov_b64 s[28:29], 0x20000
	global_load_dwordx4 v[194:197], v[182:183], off
	global_load_dwordx4 v[198:201], v[182:183], off offset:64
	global_load_dwordx4 v[202:205], v[182:183], off offset:512
	global_load_dwordx4 v[206:209], v[182:183], off offset:576
	v_lshl_add_u64 v[182:183], v[182:183], 0, s[28:29]
	s_waitcnt vmcnt(8)
	v_pk_mul_f32 v[168:169], v[168:169], s[26:27] op_sel_hi:[1,0]
	v_pk_mul_f32 v[166:167], v[166:167], s[26:27] op_sel_hi:[1,0]
	v_pk_fma_f32 v[64:65], v[64:65], v[142:143], v[168:169]
	v_pk_fma_f32 v[62:63], v[62:63], v[140:141], v[166:167]
	global_store_dwordx4 v[184:185], v[62:65], off
	v_pk_mul_f32 v[172:173], v[172:173], s[26:27] op_sel_hi:[1,0]
	v_pk_mul_f32 v[170:171], v[170:171], s[26:27] op_sel_hi:[1,0]
	v_pk_fma_f32 v[60:61], v[60:61], v[146:147], v[172:173]
	v_pk_fma_f32 v[58:59], v[58:59], v[144:145], v[170:171]
	global_store_dwordx4 v[184:185], v[58:61], off offset:64
	v_pk_mul_f32 v[176:177], v[176:177], s[26:27] op_sel_hi:[1,0]
	v_pk_mul_f32 v[174:175], v[174:175], s[26:27] op_sel_hi:[1,0]
	v_pk_fma_f32 v[56:57], v[56:57], v[150:151], v[176:177]
	v_pk_fma_f32 v[54:55], v[54:55], v[148:149], v[174:175]
	global_store_dwordx4 v[184:185], v[54:57], off offset:512
	v_pk_mul_f32 v[180:181], v[180:181], s[26:27] op_sel_hi:[1,0]
	v_pk_mul_f32 v[178:179], v[178:179], s[26:27] op_sel_hi:[1,0]
	v_pk_fma_f32 v[52:53], v[52:53], v[154:155], v[180:181]
	v_pk_fma_f32 v[50:51], v[50:51], v[152:153], v[178:179]
	global_store_dwordx4 v[184:185], v[50:53], off offset:576
	v_lshl_add_u64 v[184:185], v[184:185], 0, s[28:29]
	global_load_dwordx4 v[166:169], v[182:183], off
	global_load_dwordx4 v[170:173], v[182:183], off offset:64
	global_load_dwordx4 v[174:177], v[182:183], off offset:512
	global_load_dwordx4 v[178:181], v[182:183], off offset:576
	v_lshl_add_u64 v[182:183], v[182:183], 0, s[28:29]
	s_waitcnt vmcnt(8)
;     __device__ __forceinline__ void operator()(const f32x4 (&acc)[2][2][4][2], const Unit& u, int wr, int wc, int fr, int fq) const {
;     ...
;             for (int m = 0; m < 4; ++m) { const size_t off = (size_t)(row0 + ai * HALF + m * 16) * ldc + col0;
; #pragma unroll
;                 for (int bj = 0; bj < 2; ++bj)
; #pragma unroll
;                     for (int n = 0; n < 2; ++n) { const f32x4 xr = *(const f32x4*)(xres + off + bj * HALF + n * 16);
;                         *(f32x4*)(z + off + bj * HALF + n * 16) = xr * alpha + gv[bj][n] * acc[ai][bj][m][n]; }
;                 if (m == 3) asm volatile("" ::: "memory"); }
	v_pk_mul_f32 v[196:197], v[196:197], s[26:27] op_sel_hi:[1,0]
	v_pk_mul_f32 v[194:195], v[194:195], s[26:27] op_sel_hi:[1,0]
	v_pk_fma_f32 v[48:49], v[48:49], v[142:143], v[196:197]
	v_pk_fma_f32 v[46:47], v[46:47], v[140:141], v[194:195]
	global_store_dwordx4 v[184:185], v[46:49], off
	v_pk_mul_f32 v[200:201], v[200:201], s[26:27] op_sel_hi:[1,0]
	v_pk_mul_f32 v[198:199], v[198:199], s[26:27] op_sel_hi:[1,0]
	v_pk_fma_f32 v[44:45], v[44:45], v[146:147], v[200:201]
	v_pk_fma_f32 v[42:43], v[42:43], v[144:145], v[198:199]
	global_store_dwordx4 v[184:185], v[42:45], off offset:64
	v_pk_mul_f32 v[204:205], v[204:205], s[26:27] op_sel_hi:[1,0]
	v_pk_mul_f32 v[202:203], v[202:203], s[26:27] op_sel_hi:[1,0]
	v_pk_fma_f32 v[40:41], v[40:41], v[150:151], v[204:205]
	v_pk_fma_f32 v[38:39], v[38:39], v[148:149], v[202:203]
	global_store_dwordx4 v[184:185], v[38:41], off offset:512
	v_pk_mul_f32 v[208:209], v[208:209], s[26:27] op_sel_hi:[1,0]
	v_pk_mul_f32 v[206:207], v[206:207], s[26:27] op_sel_hi:[1,0]
	v_pk_fma_f32 v[36:37], v[36:37], v[154:155], v[208:209]
	v_pk_fma_f32 v[34:35], v[34:35], v[152:153], v[206:207]
	global_store_dwordx4 v[184:185], v[34:37], off offset:576
	v_lshl_add_u64 v[184:185], v[184:185], 0, s[28:29]
	global_load_dwordx4 v[194:197], v[182:183], off
	global_load_dwordx4 v[198:201], v[182:183], off offset:64
	global_load_dwordx4 v[202:205], v[182:183], off offset:512
	global_load_dwordx4 v[206:209], v[182:183], off offset:576
	v_lshl_add_u64 v[182:183], v[182:183], 0, s[28:29]
	s_waitcnt vmcnt(8)
	v_pk_mul_f32 v[168:169], v[168:169], s[26:27] op_sel_hi:[1,0]
	v_pk_mul_f32 v[166:167], v[166:167], s[26:27] op_sel_hi:[1,0]
	v_pk_fma_f32 v[32:33], v[32:33], v[142:143], v[168:169]
	v_pk_fma_f32 v[30:31], v[30:31], v[140:141], v[166:167]
	global_store_dwordx4 v[184:185], v[30:33], off
	v_pk_mul_f32 v[172:173], v[172:173], s[26:27] op_sel_hi:[1,0]
	v_pk_mul_f32 v[170:171], v[170:171], s[26:27] op_sel_hi:[1,0]
	v_pk_fma_f32 v[28:29], v[28:29], v[146:147], v[172:173]
	v_pk_fma_f32 v[26:27], v[26:27], v[144:145], v[170:171]
	global_store_dwordx4 v[184:185], v[26:29], off offset:64
	v_pk_mul_f32 v[176:177], v[176:177], s[26:27] op_sel_hi:[1,0]
	v_pk_mul_f32 v[174:175], v[174:175], s[26:27] op_sel_hi:[1,0]
	v_pk_fma_f32 v[24:25], v[24:25], v[150:151], v[176:177]
	v_pk_fma_f32 v[22:23], v[22:23], v[148:149], v[174:175]
	global_store_dwordx4 v[184:185], v[22:25], off offset:512
	v_pk_mul_f32 v[180:181], v[180:181], s[26:27] op_sel_hi:[1,0]
	v_pk_mul_f32 v[178:179], v[178:179], s[26:27] op_sel_hi:[1,0]
	v_pk_fma_f32 v[20:21], v[20:21], v[154:155], v[180:181]
	v_pk_fma_f32 v[18:19], v[18:19], v[152:153], v[178:179]
	global_store_dwordx4 v[184:185], v[18:21], off offset:576
	v_lshl_add_u64 v[184:185], v[184:185], 0, s[28:29]
	s_waitcnt vmcnt(4)
	v_pk_mul_f32 v[196:197], v[196:197], s[26:27] op_sel_hi:[1,0]
	v_pk_mul_f32 v[194:195], v[194:195], s[26:27] op_sel_hi:[1,0]
	v_pk_fma_f32 v[16:17], v[16:17], v[142:143], v[196:197]
	v_pk_fma_f32 v[14:15], v[14:15], v[140:141], v[194:195]
	global_store_dwordx4 v[184:185], v[14:17], off
	v_pk_mul_f32 v[200:201], v[200:201], s[26:27] op_sel_hi:[1,0]
	v_pk_mul_f32 v[198:199], v[198:199], s[26:27] op_sel_hi:[1,0]
	v_pk_fma_f32 v[12:13], v[12:13], v[146:147], v[200:201]
	v_pk_fma_f32 v[10:11], v[10:11], v[144:145], v[198:199]
	global_store_dwordx4 v[184:185], v[10:13], off offset:64
	v_pk_mul_f32 v[204:205], v[204:205], s[26:27] op_sel_hi:[1,0]
	v_pk_mul_f32 v[202:203], v[202:203], s[26:27] op_sel_hi:[1,0]
	v_pk_fma_f32 v[8:9], v[8:9], v[150:151], v[204:205]
	v_pk_fma_f32 v[6:7], v[6:7], v[148:149], v[202:203]
	global_store_dwordx4 v[184:185], v[6:9], off offset:512
	v_pk_mul_f32 v[208:209], v[208:209], s[26:27] op_sel_hi:[1,0]
	v_pk_mul_f32 v[206:207], v[206:207], s[26:27] op_sel_hi:[1,0]
	v_pk_fma_f32 v[4:5], v[4:5], v[154:155], v[208:209]
	v_pk_fma_f32 v[2:3], v[2:3], v[152:153], v[206:207]
	global_store_dwordx4 v[184:185], v[2:5], off offset:576
	s_mov_b64 s[28:29], 0x160000
	s_mov_b64 s[26:27], -1
	s_cbranch_vccnz .LBB0_1001
	s_andn2_b64 vcc, exec, s[14:15]
	s_cbranch_vccnz .LBB0_1000
	s_barrier
	s_branch .LBB0_1000

;     __device__ __forceinline__ void operator()(const f32x4 (&acc)[2][2][4][2], const Unit& u, int wr, int wc, int fr, int fq) const {
;         const int row0 = u.pm * BM + wr * 64 + fr, col0 = u.pn * BM + wc * 32 + 4 * fq;
;         f32x4 gv[2][2];
; #pragma unroll
;         for (int bj = 0; bj < 2; ++bj)
; #pragma unroll
;             for (int n = 0; n < 2; ++n) gv[bj][n] = *(const f32x4*)(gate + col0 + bj * HALF + n * 16) + 1.0f;
; #pragma unroll
;         for (int ai = 0; ai < 2; ++ai)
; #pragma unroll
;             for (int m = 0; m < 4; ++m) { const size_t off = (size_t)(row0 + ai * HALF + m * 16) * ldc + col0;
; #pragma unroll
;                 for (int bj = 0; bj < 2; ++bj)
; #pragma unroll
;                     for (int n = 0; n < 2; ++n) { const f32x4 xr = *(const f32x4*)(xres + off + bj * HALF + n * 16);
;                         *(f32x4*)(z + off + bj * HALF + n * 16) = xr * alpha + gv[bj][n] * acc[ai][bj][m][n]; }
;                 if (m == 3) asm volatile("" ::: "memory"); }
.LBB0_1271:
	v_lshl_or_b32 v158, s58, 8, v164
	v_ashrrev_i32_e32 v159, 31, v158
	v_lshl_add_u64 v[156:157], v[158:159], 2, s[16:17]
	global_load_dwordx4 v[140:143], v[156:157], off
	global_load_dwordx4 v[144:147], v[156:157], off offset:64
	global_load_dwordx4 v[148:151], v[156:157], off offset:512
	global_load_dwordx4 v[152:155], v[156:157], off offset:576
	v_lshl_add_u32 v160, s57, 8, v162
	v_ashrrev_i32_e32 v161, 31, v160
	s_mov_b32 s26, 0x3fb504f3
	s_and_b64 vcc, exec, s[4:5]
	v_lshlrev_b64 v[156:157], 11, v[160:161]
	v_lshl_add_u64 v[156:157], v[156:157], 0, v[158:159]
	v_lshlrev_b64 v[156:157], 2, v[156:157]
	v_lshl_add_u64 v[182:183], s[14:15], 0, v[156:157]
	v_lshl_add_u64 v[184:185], s[14:15], 0, v[156:157]
	s_mov_b64 s[24:25], 0x20000
	global_load_dwordx4 v[166:169], v[182:183], off
	global_load_dwordx4 v[170:173], v[182:183], off offset:64
	global_load_dwordx4 v[174:177], v[182:183], off offset:512
	global_load_dwordx4 v[178:181], v[182:183], off offset:576
	v_lshl_add_u64 v[182:183], v[182:183], 0, s[24:25]
	global_load_dwordx4 v[194:197], v[182:183], off
	global_load_dwordx4 v[198:201], v[182:183], off offset:64
	global_load_dwordx4 v[202:205], v[182:183], off offset:512
	global_load_dwordx4 v[206:209], v[182:183], off offset:576
	v_lshl_add_u64 v[182:183], v[182:183], 0, s[24:25]
	s_waitcnt vmcnt(8)
	v_pk_add_f32 v[140:141], v[140:141], 1.0 op_sel_hi:[1,0]
	v_pk_add_f32 v[142:143], v[142:143], 1.0 op_sel_hi:[1,0]
	v_pk_add_f32 v[144:145], v[144:145], 1.0 op_sel_hi:[1,0]
	v_pk_add_f32 v[146:147], v[146:147], 1.0 op_sel_hi:[1,0]
	v_pk_add_f32 v[148:149], v[148:149], 1.0 op_sel_hi:[1,0]
	v_pk_add_f32 v[150:151], v[150:151], 1.0 op_sel_hi:[1,0]
	v_pk_add_f32 v[152:153], v[152:153], 1.0 op_sel_hi:[1,0]
	v_pk_add_f32 v[154:155], v[154:155], 1.0 op_sel_hi:[1,0]
	s_waitcnt vmcnt(4)
	v_pk_mul_f32 v[168:169], v[168:169], s[26:27] op_sel_hi:[1,0]
	v_pk_mul_f32 v[166:167], v[166:167], s[26:27] op_sel_hi:[1,0]
	v_pk_fma_f32 v[128:129], v[128:129], v[142:143], v[168:169]
	v_pk_fma_f32 v[126:127], v[126:127], v[140:141], v[166:167]
	global_store_dwordx4 v[184:185], v[126:129], off
	v_pk_mul_f32 v[172:173], v[172:173], s[26:27] op_sel_hi:[1,0]
	v_pk_mul_f32 v[170:171], v[170:171], s[26:27] op_sel_hi:[1,0]
	v_pk_fma_f32 v[124:125], v[124:125], v[146:147], v[172:173]
	v_pk_fma_f32 v[122:123], v[122:123], v[144:145], v[170:171]
	global_store_dwordx4 v[184:185], v[122:125], off offset:64
	v_pk_mul_f32 v[176:177], v[176:177], s[26:27] op_sel_hi:[1,0]
	v_pk_mul_f32 v[174:175], v[174:175], s[26:27] op_sel_hi:[1,0]
	v_pk_fma_f32 v[120:121], v[120:121], v[150:151], v[176:177]
	v_pk_fma_f32 v[118:119], v[118:119], v[148:149], v[174:175]
	global_store_dwordx4 v[184:185], v[118:121], off offset:512
	v_pk_mul_f32 v[180:181], v[180:181], s[26:27] op_sel_hi:[1,0]
	v_pk_mul_f32 v[178:179], v[178:179], s[26:27] op_sel_hi:[1,0]
	v_pk_fma_f32 v[116:117], v[116:117], v[154:155], v[180:181]
	v_pk_fma_f32 v[114:115], v[114:115], v[152:153], v[178:179]
	global_store_dwordx4 v[184:185], v[114:117], off offset:576
	v_lshl_add_u64 v[184:185], v[184:185], 0, s[24:25]
	global_load_dwordx4 v[166:169], v[182:183], off
	global_load_dwordx4 v[170:173], v[182:183], off offset:64
	global_load_dwordx4 v[174:177], v[182:183], off offset:512
	global_load_dwordx4 v[178:181], v[182:183], off offset:576
	v_lshl_add_u64 v[182:183], v[182:183], 0, s[24:25]
	s_waitcnt vmcnt(8)
	v_pk_mul_f32 v[196:197], v[196:197], s[26:27] op_sel_hi:[1,0]
	v_pk_mul_f32 v[194:195], v[194:195], s[26:27] op_sel_hi:[1,0]
	v_pk_fma_f32 v[112:113], v[112:113], v[142:143], v[196:197]
	v_pk_fma_f32 v[110:111], v[110:111], v[140:141], v[194:195]
	global_store_dwordx4 v[184:185], v[110:113], off
	v_pk_mul_f32 v[200:201], v[200:201], s[26:27] op_sel_hi:[1,0]
	v_pk_mul_f32 v[198:199], v[198:199], s[26:27] op_sel_hi:[1,0]
	v_pk_fma_f32 v[108:109], v[108:109], v[146:147], v[200:201]
	v_pk_fma_f32 v[106:107], v[106:107], v[144:145], v[198:199]
	global_store_dwordx4 v[184:185], v[106:109], off offset:64
	v_pk_mul_f32 v[204:205], v[204:205], s[26:27] op_sel_hi:[1,0]
	v_pk_mul_f32 v[202:203], v[202:203], s[26:27] op_sel_hi:[1,0]
	v_pk_fma_f32 v[104:105], v[104:105], v[150:151], v[204:205]
	v_pk_fma_f32 v[102:103], v[102:103], v[148:149], v[202:203]
	global_store_dwordx4 v[184:185], v[102:105], off offset:512
	v_pk_mul_f32 v[208:209], v[208:209], s[26:27] op_sel_hi:[1,0]
	v_pk_mul_f32 v[206:207], v[206:207], s[26:27] op_sel_hi:[1,0]
	v_pk_fma_f32 v[100:101], v[100:101], v[154:155], v[208:209]
	v_pk_fma_f32 v[98:99], v[98:99], v[152:153], v[206:207]
	global_store_dwordx4 v[184:185], v[98:101], off offset:576
	v_lshl_add_u64 v[184:185], v[184:185], 0, s[24:25]
	global_load_dwordx4 v[194:197], v[182:183], off
	global_load_dwordx4 v[198:201], v[182:183], off offset:64
	global_load_dwordx4 v[202:205], v[182:183], off offset:512
	global_load_dwordx4 v[206:209], v[182:183], off offset:576
	s_mov_b64 s[24:25], 0xa0000
	v_lshl_add_u64 v[182:183], v[182:183], 0, s[24:25]
	s_mov_b64 s[24:25], 0x20000
	s_waitcnt vmcnt(8)
;     __device__ __forceinline__ void operator()(const f32x4 (&acc)[2][2][4][2], const Unit& u, int wr, int wc, int fr, int fq) const {
;     ...
;             for (int m = 0; m < 4; ++m) { const size_t off = (size_t)(row0 + ai * HALF + m * 16) * ldc + col0;
; #pragma unroll
;                 for (int bj = 0; bj < 2; ++bj)
; #pragma unroll
;                     for (int n = 0; n < 2; ++n) { const f32x4 xr = *(const f32x4*)(xres + off + bj * HALF + n * 16);
;                         *(f32x4*)(z + off + bj * HALF + n * 16) = xr * alpha + gv[bj][n] * acc[ai][bj][m][n]; }
	v_pk_mul_f32 v[168:169], v[168:169], s[26:27] op_sel_hi:[1,0]
	v_pk_mul_f32 v[166:167], v[166:167], s[26:27] op_sel_hi:[1,0]
	v_pk_fma_f32 v[96:97], v[96:97], v[142:143], v[168:169]
	v_pk_fma_f32 v[94:95], v[94:95], v[140:141], v[166:167]
	global_store_dwordx4 v[184:185], v[94:97], off
	v_pk_mul_f32 v[172:173], v[172:173], s[26:27] op_sel_hi:[1,0]
	v_pk_mul_f32 v[170:171], v[170:171], s[26:27] op_sel_hi:[1,0]
	v_pk_fma_f32 v[92:93], v[92:93], v[146:147], v[172:173]
	v_pk_fma_f32 v[90:91], v[90:91], v[144:145], v[170:171]
	global_store_dwordx4 v[184:185], v[90:93], off offset:64
	v_pk_mul_f32 v[176:177], v[176:177], s[26:27] op_sel_hi:[1,0]
	v_pk_mul_f32 v[174:175], v[174:175], s[26:27] op_sel_hi:[1,0]
	v_pk_fma_f32 v[88:89], v[88:89], v[150:151], v[176:177]
	v_pk_fma_f32 v[86:87], v[86:87], v[148:149], v[174:175]
	global_store_dwordx4 v[184:185], v[86:89], off offset:512
	v_pk_mul_f32 v[180:181], v[180:181], s[26:27] op_sel_hi:[1,0]
	v_pk_mul_f32 v[178:179], v[178:179], s[26:27] op_sel_hi:[1,0]
	v_pk_fma_f32 v[84:85], v[84:85], v[154:155], v[180:181]
	v_pk_fma_f32 v[82:83], v[82:83], v[152:153], v[178:179]
	global_store_dwordx4 v[184:185], v[82:85], off offset:576
	v_lshl_add_u64 v[184:185], v[184:185], 0, s[24:25]
	global_load_dwordx4 v[166:169], v[182:183], off
	global_load_dwordx4 v[170:173], v[182:183], off offset:64
	global_load_dwordx4 v[174:177], v[182:183], off offset:512
	global_load_dwordx4 v[178:181], v[182:183], off offset:576
	v_lshl_add_u64 v[182:183], v[182:183], 0, s[24:25]
	s_waitcnt vmcnt(8)
	v_pk_mul_f32 v[196:197], v[196:197], s[26:27] op_sel_hi:[1,0]
	v_pk_mul_f32 v[194:195], v[194:195], s[26:27] op_sel_hi:[1,0]
	v_pk_fma_f32 v[80:81], v[80:81], v[142:143], v[196:197]
	v_pk_fma_f32 v[78:79], v[78:79], v[140:141], v[194:195]
	global_store_dwordx4 v[184:185], v[78:81], off
	v_pk_mul_f32 v[200:201], v[200:201], s[26:27] op_sel_hi:[1,0]
	v_pk_mul_f32 v[198:199], v[198:199], s[26:27] op_sel_hi:[1,0]
	v_pk_fma_f32 v[76:77], v[76:77], v[146:147], v[200:201]
	v_pk_fma_f32 v[74:75], v[74:75], v[144:145], v[198:199]
	global_store_dwordx4 v[184:185], v[74:77], off offset:64
	v_pk_mul_f32 v[204:205], v[204:205], s[26:27] op_sel_hi:[1,0]
	v_pk_mul_f32 v[202:203], v[202:203], s[26:27] op_sel_hi:[1,0]
	v_pk_fma_f32 v[72:73], v[72:73], v[150:151], v[204:205]
	v_pk_fma_f32 v[70:71], v[70:71], v[148:149], v[202:203]
	global_store_dwordx4 v[184:185], v[70:73], off offset:512
	v_pk_mul_f32 v[208:209], v[208:209], s[26:27] op_sel_hi:[1,0]
	v_pk_mul_f32 v[206:207], v[206:207], s[26:27] op_sel_hi:[1,0]
	v_pk_fma_f32 v[68:69], v[68:69], v[154:155], v[208:209]
	v_pk_fma_f32 v[66:67], v[66:67], v[152:153], v[206:207]
	global_store_dwordx4 v[184:185], v[66:69], off offset:576
	s_mov_b64 s[24:25], 0xa0000
	v_lshl_add_u64 v[184:185], v[184:185], 0, s[24:25]
	s_mov_b64 s[24:25], 0x20000
	global_load_dwordx4 v[194:197], v[182:183], off
	global_load_dwordx4 v[198:201], v[182:183], off offset:64
	global_load_dwordx4 v[202:205], v[182:183], off offset:512
	global_load_dwordx4 v[206:209], v[182:183], off offset:576
	v_lshl_add_u64 v[182:183], v[182:183], 0, s[24:25]
	s_waitcnt vmcnt(8)
	v_pk_mul_f32 v[168:169], v[168:169], s[26:27] op_sel_hi:[1,0]
	v_pk_mul_f32 v[166:167], v[166:167], s[26:27] op_sel_hi:[1,0]
	v_pk_fma_f32 v[64:65], v[64:65], v[142:143], v[168:169]
	v_pk_fma_f32 v[62:63], v[62:63], v[140:141], v[166:167]
	global_store_dwordx4 v[184:185], v[62:65], off
	v_pk_mul_f32 v[172:173], v[172:173], s[26:27] op_sel_hi:[1,0]
	v_pk_mul_f32 v[170:171], v[170:171], s[26:27] op_sel_hi:[1,0]
	v_pk_fma_f32 v[60:61], v[60:61], v[146:147], v[172:173]
	v_pk_fma_f32 v[58:59], v[58:59], v[144:145], v[170:171]
	global_store_dwordx4 v[184:185], v[58:61], off offset:64
	v_pk_mul_f32 v[176:177], v[176:177], s[26:27] op_sel_hi:[1,0]
	v_pk_mul_f32 v[174:175], v[174:175], s[26:27] op_sel_hi:[1,0]
	v_pk_fma_f32 v[56:57], v[56:57], v[150:151], v[176:177]
	v_pk_fma_f32 v[54:55], v[54:55], v[148:149], v[174:175]
	global_store_dwordx4 v[184:185], v[54:57], off offset:512
	v_pk_mul_f32 v[180:181], v[180:181], s[26:27] op_sel_hi:[1,0]
	v_pk_mul_f32 v[178:179], v[178:179], s[26:27] op_sel_hi:[1,0]
	v_pk_fma_f32 v[52:53], v[52:53], v[154:155], v[180:181]
	v_pk_fma_f32 v[50:51], v[50:51], v[152:153], v[178:179]
	global_store_dwordx4 v[184:185], v[50:53], off offset:576
	v_lshl_add_u64 v[184:185], v[184:185], 0, s[24:25]
	global_load_dwordx4 v[166:169], v[182:183], off
	global_load_dwordx4 v[170:173], v[182:183], off offset:64
	global_load_dwordx4 v[174:177], v[182:183], off offset:512
	global_load_dwordx4 v[178:181], v[182:183], off offset:576
	v_lshl_add_u64 v[182:183], v[182:183], 0, s[24:25]
	s_waitcnt vmcnt(8)
;     __device__ __forceinline__ void operator()(const f32x4 (&acc)[2][2][4][2], const Unit& u, int wr, int wc, int fr, int fq) const {
;     ...
;             for (int m = 0; m < 4; ++m) { const size_t off = (size_t)(row0 + ai * HALF + m * 16) * ldc + col0;
; #pragma unroll
;                 for (int bj = 0; bj < 2; ++bj)
; #pragma unroll
;                     for (int n = 0; n < 2; ++n) { const f32x4 xr = *(const f32x4*)(xres + off + bj * HALF + n * 16);
;                         *(f32x4*)(z + off + bj * HALF + n * 16) = xr * alpha + gv[bj][n] * acc[ai][bj][m][n]; }
;                 if (m == 3) asm volatile("" ::: "memory"); }
	v_pk_mul_f32 v[196:197], v[196:197], s[26:27] op_sel_hi:[1,0]
	v_pk_mul_f32 v[194:195], v[194:195], s[26:27] op_sel_hi:[1,0]
	v_pk_fma_f32 v[48:49], v[48:49], v[142:143], v[196:197]
	v_pk_fma_f32 v[46:47], v[46:47], v[140:141], v[194:195]
	global_store_dwordx4 v[184:185], v[46:49], off
	v_pk_mul_f32 v[200:201], v[200:201], s[26:27] op_sel_hi:[1,0]
	v_pk_mul_f32 v[198:199], v[198:199], s[26:27] op_sel_hi:[1,0]
	v_pk_fma_f32 v[44:45], v[44:45], v[146:147], v[200:201]
	v_pk_fma_f32 v[42:43], v[42:43], v[144:145], v[198:199]
	global_store_dwordx4 v[184:185], v[42:45], off offset:64
	v_pk_mul_f32 v[204:205], v[204:205], s[26:27] op_sel_hi:[1,0]
	v_pk_mul_f32 v[202:203], v[202:203], s[26:27] op_sel_hi:[1,0]
	v_pk_fma_f32 v[40:41], v[40:41], v[150:151], v[204:205]
	v_pk_fma_f32 v[38:39], v[38:39], v[148:149], v[202:203]
	global_store_dwordx4 v[184:185], v[38:41], off offset:512
	v_pk_mul_f32 v[208:209], v[208:209], s[26:27] op_sel_hi:[1,0]
	v_pk_mul_f32 v[206:207], v[206:207], s[26:27] op_sel_hi:[1,0]
	v_pk_fma_f32 v[36:37], v[36:37], v[154:155], v[208:209]
	v_pk_fma_f32 v[34:35], v[34:35], v[152:153], v[206:207]
	global_store_dwordx4 v[184:185], v[34:37], off offset:576
	v_lshl_add_u64 v[184:185], v[184:185], 0, s[24:25]
	global_load_dwordx4 v[194:197], v[182:183], off
	global_load_dwordx4 v[198:201], v[182:183], off offset:64
	global_load_dwordx4 v[202:205], v[182:183], off offset:512
	global_load_dwordx4 v[206:209], v[182:183], off offset:576
	v_lshl_add_u64 v[182:183], v[182:183], 0, s[24:25]
	s_waitcnt vmcnt(8)
	v_pk_mul_f32 v[168:169], v[168:169], s[26:27] op_sel_hi:[1,0]
	v_pk_mul_f32 v[166:167], v[166:167], s[26:27] op_sel_hi:[1,0]
	v_pk_fma_f32 v[32:33], v[32:33], v[142:143], v[168:169]
	v_pk_fma_f32 v[30:31], v[30:31], v[140:141], v[166:167]
	global_store_dwordx4 v[184:185], v[30:33], off
	v_pk_mul_f32 v[172:173], v[172:173], s[26:27] op_sel_hi:[1,0]
	v_pk_mul_f32 v[170:171], v[170:171], s[26:27] op_sel_hi:[1,0]
	v_pk_fma_f32 v[28:29], v[28:29], v[146:147], v[172:173]
	v_pk_fma_f32 v[26:27], v[26:27], v[144:145], v[170:171]
	global_store_dwordx4 v[184:185], v[26:29], off offset:64
	v_pk_mul_f32 v[176:177], v[176:177], s[26:27] op_sel_hi:[1,0]
	v_pk_mul_f32 v[174:175], v[174:175], s[26:27] op_sel_hi:[1,0]
	v_pk_fma_f32 v[24:25], v[24:25], v[150:151], v[176:177]
	v_pk_fma_f32 v[22:23], v[22:23], v[148:149], v[174:175]
	global_store_dwordx4 v[184:185], v[22:25], off offset:512
	v_pk_mul_f32 v[180:181], v[180:181], s[26:27] op_sel_hi:[1,0]
	v_pk_mul_f32 v[178:179], v[178:179], s[26:27] op_sel_hi:[1,0]
	v_pk_fma_f32 v[20:21], v[20:21], v[154:155], v[180:181]
	v_pk_fma_f32 v[18:19], v[18:19], v[152:153], v[178:179]
	global_store_dwordx4 v[184:185], v[18:21], off offset:576
	v_lshl_add_u64 v[184:185], v[184:185], 0, s[24:25]
	s_waitcnt vmcnt(4)
	v_pk_mul_f32 v[196:197], v[196:197], s[26:27] op_sel_hi:[1,0]
	v_pk_mul_f32 v[194:195], v[194:195], s[26:27] op_sel_hi:[1,0]
	v_pk_fma_f32 v[16:17], v[16:17], v[142:143], v[196:197]
	v_pk_fma_f32 v[14:15], v[14:15], v[140:141], v[194:195]
	global_store_dwordx4 v[184:185], v[14:17], off
	v_pk_mul_f32 v[200:201], v[200:201], s[26:27] op_sel_hi:[1,0]
	v_pk_mul_f32 v[198:199], v[198:199], s[26:27] op_sel_hi:[1,0]
	v_pk_fma_f32 v[12:13], v[12:13], v[146:147], v[200:201]
	v_pk_fma_f32 v[10:11], v[10:11], v[144:145], v[198:199]
	global_store_dwordx4 v[184:185], v[10:13], off offset:64
	v_pk_mul_f32 v[204:205], v[204:205], s[26:27] op_sel_hi:[1,0]
	v_pk_mul_f32 v[202:203], v[202:203], s[26:27] op_sel_hi:[1,0]
	v_pk_fma_f32 v[8:9], v[8:9], v[150:151], v[204:205]
	v_pk_fma_f32 v[6:7], v[6:7], v[148:149], v[202:203]
	global_store_dwordx4 v[184:185], v[6:9], off offset:512
	v_pk_mul_f32 v[208:209], v[208:209], s[26:27] op_sel_hi:[1,0]
	v_pk_mul_f32 v[206:207], v[206:207], s[26:27] op_sel_hi:[1,0]
	v_pk_fma_f32 v[4:5], v[4:5], v[154:155], v[208:209]
	v_pk_fma_f32 v[2:3], v[2:3], v[152:153], v[206:207]
	global_store_dwordx4 v[184:185], v[2:5], off offset:576
	s_mov_b64 s[24:25], -1
	s_cbranch_vccnz .LBB0_1255
	s_andn2_b64 vcc, exec, s[12:13]
	s_cbranch_vccnz .LBB0_1254
	s_barrier
	s_branch .LBB0_1254
